# G3: gla_norm loaded once ahead of the item loop (was 8 dependent loads per item), the item's four vT fragments requested at item start
# speedup vs baseline: 1.0030x; 1.0030x over previous
; #define G3_LOAD_S(it_) do { _Pragma("unroll") for (int s_ = 0; s_ < 4; ++s_) _Pragma("unroll") for (int nt_ = 0; nt_ < 2; ++nt_) \
;         sfp[s_][nt_] = *(const bf16x8*)(SpT + ((size_t)(it_) * 256 + 32 * wid + 16 * nt_ + fr) * 128 + 32 * s_ + 8 * fq); } while (0)
; __device__ __forceinline__ void gla_g3(const Params& P, unsigned char* lds) {
;     const int tid = threadIdx.x, wid = tid >> 6, lane = tid & 63, fr = lane & 15, fq = lane >> 4;
;     const bf16_t* qg = (const bf16_t*)(P.ws + O_Q); const bf16_t* kg = (const bf16_t*)(P.ws + O_K); const bf16_t* gg = (const bf16_t*)(P.ws + O_G);
;     const bf16_t* vT = (const bf16_t*)(P.ws + O_VT); const bf16_t* SpT = (const bf16_t*)(P.ws + O_KVT); bf16_t* og = (bf16_t*)(P.ws + O_OG);
;     const float* bsh = (const float*)(lds + L_BSH); bf16_t* qd = (bf16_t*)(lds + L_QD); bf16_t* kin = (bf16_t*)(lds + L_KIN); bf16_t* Psh = (bf16_t*)(lds + L_PSH); float* ssh = (float*)(lds + L_SSQ);
;     bf16x8 sfp[4][2];
;     ...
;     if ((int)blockIdx.x < NITEM) G3_LOAD_S(blockIdx.x);
;     ...
;                     const u32x2 gw = gwp[lt][nt]; const f32x4 nw = *(const f32x4*)(P.in[16] + dvh);
.LBB0_2139:
	s_andn2_b64 vcc, exec, s[6:7]
	v_lshrrev_b32_e32 v102, 4, v210
	s_cbranch_vccnz .LBB0_2181
	v_lshlrev_b32_e32 v33, 3, v210
	v_and_b32_e32 v33, 0x78, v33
	v_lshlrev_b32_e32 v64, 1, v33
	v_mov_b32_e32 v65, 0
	v_lshl_add_u64 v[38:39], s[44:45], 0, v[64:65]
	s_mov_b64 s[16:17], 0x510dc00
	s_add_u32 s3, s44, 0x9a2dc00
	v_lshrrev_b32_e32 v40, 7, v210
	v_lshl_add_u64 v[66:67], v[38:39], 0, s[16:17]
	s_mov_b64 s[16:17], 0x614dc00
	s_addc_u32 s78, s45, 0
	v_lshlrev_b32_e32 v108, 4, v40
	v_lshl_add_u64 v[68:69], v[38:39], 0, s[16:17]
	v_lshl_add_u32 v38, v33, 2, 0
	v_lshlrev_b32_e32 v33, 1, v36
	s_add_u32 s79, s44, 0x308dc00
	v_and_b32_e32 v57, 2, v33
	v_or_b32_e32 v33, v108, v103
	v_add_u32_e32 v60, 0, v32
	s_movk_i32 s16, 0x110
	s_addc_u32 s80, s45, 0
	s_add_i32 s46, 0, 0x14400
	v_mad_u32_u24 v127, v33, s16, v60
	v_mov_b32_e32 v33, v65
	v_lshl_add_u32 v104, v103, 2, s46
	v_sub_u32_e32 v39, v38, v64
	v_lshl_add_u64 v[72:73], s[14:15], 0, v[32:33]
	v_and_b32_e32 v33, 0x3c0, v210
	v_lshlrev_b32_e32 v64, 6, v36
	v_lshlrev_b32_e32 v58, 2, v37
	v_lshlrev_b32_e32 v70, 3, v37
	v_mov_b32_e32 v71, v65
	v_cmp_eq_u32_e64 s[14:15], 0, v37
	v_lshl_add_u32 v129, v33, 2, v104
	v_lshl_add_u64 v[36:37], s[44:45], 0, v[64:65]
	v_mul_u32_u24_e32 v33, 0x88, v102
	v_lshl_add_u64 v[36:37], v[36:37], 0, v[70:71]
	v_lshl_add_u32 v71, v33, 1, v39
	v_add_u32_e32 v33, 0x200, v210
	v_lshrrev_b32_e32 v130, 4, v33
	v_lshlrev_b32_e32 v35, 4, v210
	v_and_b32_e32 v107, 0x7f, v210
	s_mov_b64 s[16:17], 0x79adc00
	v_mul_u32_u24_e32 v33, 0x88, v130
	s_add_i32 s30, 0, 0x12000
	v_or_b32_e32 v135, 32, v70
	s_mov_b64 s[20:21], 0x80
	s_load_dwordx4 s[40:43], s[0:1], 0x70
	s_load_dwordx2 s[38:39], s[0:1], 0x80
	v_lshl_add_u32 v125, v107, 2, 0
	v_lshl_add_u64 v[74:75], v[36:37], 0, s[16:17]
	v_lshl_add_u32 v131, v33, 1, v39
	v_cmp_le_u32_e64 s[16:17], v57, v40
	v_lshl_or_b32 v39, v57, 4, v103
	v_cmp_lt_u32_e64 s[18:19], v57, v40
	v_add_u32_e32 v57, s30, v32
	v_mul_u32_u24_e32 v88, 0x90, v103
	v_lshlrev_b32_e32 v32, 1, v135
	v_lshl_add_u64 v[78:79], v[72:73], 0, s[20:21]
	s_mov_b64 s[20:21], 0xc0
	v_and_b32_e32 v64, 48, v35
	v_lshlrev_b32_e32 v41, 10, v40
	v_lshl_add_u32 v126, v40, 13, v125
	v_or_b32_e32 v59, v58, v108
	v_or_b32_e32 v40, 16, v39
	v_add3_u32 v136, s30, v88, v32
	v_lshl_add_u64 v[80:81], v[72:73], 0, s[20:21]
	v_lshl_add_u64 v[32:33], s[44:45], 0, v[64:65]
	s_mov_b64 s[20:21], 0x2e88000
	v_or_b32_e32 v109, 1, v108
	v_or_b32_e32 v110, 2, v108
	v_or_b32_e32 v111, 3, v108
	v_or_b32_e32 v112, 4, v108
	v_or_b32_e32 v113, 5, v108
	v_or_b32_e32 v114, 6, v108
	v_or_b32_e32 v115, 7, v108
	v_or_b32_e32 v116, 8, v108
	v_or_b32_e32 v117, 9, v108
	v_or_b32_e32 v118, 10, v108
	v_or_b32_e32 v119, 11, v108
	v_or_b32_e32 v120, 12, v108
	v_or_b32_e32 v121, 13, v108
	v_or_b32_e32 v122, 14, v108
	v_or_b32_e32 v123, 15, v108
	v_or_b32_e32 v128, v34, v103
	v_or_b32_e32 v34, v58, v34
	v_mul_u32_u24_e32 v61, 0x90, v59
	v_or_b32_e32 v132, 16, v103
	v_lshl_add_u64 v[82:83], v[32:33], 0, s[20:21]
	v_lshl_add_u32 v32, v39, 1, s30
	v_lshlrev_b32_e32 v33, 1, v40
	s_movk_i32 s6, 0x100
	s_movk_i32 s8, 0x7f
	v_lshlrev_b32_e32 v42, 6, v109
	v_lshlrev_b32_e32 v43, 6, v110
	v_lshlrev_b32_e32 v44, 6, v111
	v_lshlrev_b32_e32 v45, 6, v112
	v_lshlrev_b32_e32 v46, 6, v113
	v_lshlrev_b32_e32 v47, 6, v114
	v_lshlrev_b32_e32 v48, 6, v115
	v_lshlrev_b32_e32 v49, 6, v116
	v_lshlrev_b32_e32 v50, 6, v117
	v_lshlrev_b32_e32 v51, 6, v118
	v_lshlrev_b32_e32 v52, 6, v119
	v_lshlrev_b32_e32 v53, 6, v120
	v_lshlrev_b32_e32 v54, 6, v121
	v_lshlrev_b32_e32 v55, 6, v122
	v_lshlrev_b32_e32 v56, 6, v123
	s_movk_i32 s10, 0xff
	s_movk_i32 s12, 0x17f
	v_lshlrev_b32_e32 v36, 9, v102
	v_lshlrev_b32_e32 v37, 9, v130
	v_mul_u32_u24_e32 v58, 0x110, v39
	v_or_b32_e32 v62, 1, v59
	v_or_b32_e32 v63, 2, v59
	v_or_b32_e32 v84, 3, v59
	v_or_b32_e32 v133, 32, v103
	v_or_b32_e32 v134, 48, v103
	v_mul_u32_u24_e32 v89, 0x110, v103
	v_add3_u32 v140, s30, v61, v33
	v_mul_u32_u24_e32 v33, 0x110, v132
	v_lshlrev_b32_e32 v64, 2, v34
	v_add_u32_e32 v165, v32, v61
	v_mbcnt_lo_u32_b32 v32, -1, 0
	s_mov_b32 s84, s96
	s_mov_b64 s[96:97], s[94:95]
	s_mov_b32 s47, 0
	v_cmp_gt_u32_e64 s[6:7], s6, v210
	v_lshrrev_b32_e32 v105, 2, v210
	v_add_u32_e32 v106, 0, v35
	v_lshl_add_u32 v124, v210, 2, 0
	v_cmp_lt_u32_e64 s[8:9], s8, v210
	v_cmp_lt_u32_e64 s[10:11], s10, v210
	v_cmp_lt_u32_e64 s[12:13], s12, v210
	v_add_u32_e32 v137, 0x900, v136
	v_add_u32_e32 v138, 0x1200, v136
	v_add_u32_e32 v139, 0x1b00, v136
	v_lshl_add_u64 v[76:77], v[72:73], 0, 64
	v_cmp_gt_u32_e64 s[20:21], v39, v59
	v_cmp_gt_u32_e64 s[22:23], v39, v62
	v_cmp_gt_u32_e64 s[24:25], v39, v63
	v_cmp_gt_u32_e64 s[26:27], v39, v84
	v_cmp_gt_u32_e64 s[28:29], v40, v59
	v_cmp_gt_u32_e64 s[30:31], v40, v62
	v_add_u32_e32 v141, 0x90, v140
	v_cmp_gt_u32_e64 s[34:35], v40, v63
	v_add_u32_e32 v142, 0x120, v140
	v_cmp_gt_u32_e64 s[36:37], v40, v84
	v_add_u32_e32 v143, 0x1b0, v140
	v_lshlrev_b32_e32 v84, 8, v128
	v_mov_b32_e32 v85, v65
	s_waitcnt lgkmcnt(0)
	v_lshl_add_u64 v[86:87], s[38:39], 0, v[64:65]
	global_load_dwordx4 v[212:215], v[86:87], off
	global_load_dwordx4 v[216:219], v[86:87], off offset:64
	v_lshl_add_u32 v144, v132, 2, s46
	v_lshl_add_u32 v145, v133, 2, s46
	v_lshl_add_u32 v146, v134, 2, s46
	s_lshl_b32 s81, s2, 2
	s_lshl_b32 s82, s58, 2
	s_lshl_b32 s83, s2, 4
	s_lshl_b32 s85, s58, 4
	s_lshl_b32 s86, s2, 6
	s_lshl_b32 s87, s58, 6
	s_movk_i32 s88, 0x3000
	v_add_u32_e32 v147, 0, v41
	s_mov_b32 s89, 0xbfb8aa3b
	s_mov_b32 s90, 0x800000
	s_mov_b32 s91, 0x3f317217
	s_mov_b32 s92, 0x7f800000
	s_mov_b32 s93, 0x3d800000
	v_add_u32_e32 v148, 0, v42
	v_add_u32_e32 v149, 0, v43
	v_add_u32_e32 v150, 0, v44
	v_add_u32_e32 v151, 0, v45
	v_add_u32_e32 v152, 0, v46
	v_add_u32_e32 v153, 0, v47
	v_add_u32_e32 v154, 0, v48
	v_add_u32_e32 v155, 0, v49
	v_add_u32_e32 v156, 0, v50
	v_add_u32_e32 v157, 0, v51
	v_add_u32_e32 v158, 0, v52
	v_add_u32_e32 v159, 0, v53
	v_add_u32_e32 v160, 0, v54
	v_add_u32_e32 v161, 0, v55
	v_add_u32_e32 v162, 0, v56
	v_add_u32_e32 v163, v38, v36
	v_add_u32_e32 v164, v38, v37
	s_mov_b32 s94, 0x82000
	v_add_u32_e32 v166, v57, v88
	v_add_u32_e32 v167, v60, v89
	v_add_u32_e32 v168, v60, v33
	v_mov_b32_e32 v169, 0x358637bd
	v_lshlrev_b32_e32 v88, 1, v34
	v_mov_b32_e32 v170, 0x41b17218
	v_add_u32_e32 v171, v60, v58
	v_mbcnt_hi_u32_b32 v172, -1, v32
	s_mov_b32 s48, s2
	s_and_b32 s38, s2, 7
	s_lshr_b32 s39, s2, 3
	s_lshr_b32 s60, s38, 1
	s_lshl_b32 s60, s60, 8
	s_and_b32 s38, s38, 1
	s_lshl_b32 s38, s38, 5
	s_add_i32 s38, s38, s39
	s_or_b32 s60, s60, s38
	s_cmpk_eq_i32 s58, 0x100
	s_cselect_b32 s48, s60, s2
	s_lshl_b32 s81, s48, 2
	s_lshl_b32 s83, s48, 4
	s_lshl_b32 s86, s48, 6
	s_branch .LBB0_2142

; __device__ __forceinline__ unsigned cvt_pk_bf16(float lo, float hi) { unsigned r; asm volatile("v_cvt_pk_bf16_f32 %0, %1, %2" : "=v"(r) : "v"(lo), "v"(hi)); return r; }
; __device__ __forceinline__ void gla_g3(const Params& P, unsigned char* lds) {
;     ...
;                 for (int j = 0; j < 4; ++j) { const int l = 16 * lt + 4 * fq + j; const float pv = (mcol <= l) ? a4[j] : 0.f; Psh[l * 72 + mcol] = (bf16_t)(cvt_pk_bf16(pv, 0.f) & 0xffffu); } } }
;         __syncthreads();
;         f32x4 acc[2][4];
; #pragma unroll
;         for (int nt = 0; nt < 2; ++nt)
; #pragma unroll
;             for (int lt = 0; lt < 4; ++lt) acc[nt][lt] = (f32x4){0.f, 0.f, 0.f, 0.f};
; #pragma unroll
;         for (int s = 0; s < 2; ++s) { const int t8 = 32 * s + 8 * fq;
;             if (32 * s < I.L) {
;                 bf16x8 vf[2];
; #pragma unroll
;                 for (int nt = 0; nt < 2; ++nt) { const int tc = t8 < I.L ? t8 : 0; vf[nt] = *(const bf16x8*)(vT + (size_t)(I.h * DV + 32 * wid + 16 * nt + fr) * MPAD + I.row0 + tc); if (t8 >= I.L) vf[nt] = (bf16x8){0, 0, 0, 0, 0, 0, 0, 0}; }
; #pragma unroll
;                 for (int lt = 0; lt < 4; ++lt) { const bf16x8 pf = *(const bf16x8*)(Psh + (16 * lt + fr) * 72 + t8);
;                     acc[0][lt] = __builtin_amdgcn_mfma_f32_16x16x32_bf16(vf[0], pf, acc[0][lt], 0, 0, 0); acc[1][lt] = __builtin_amdgcn_mfma_f32_16x16x32_bf16(vf[1], pf, acc[1][lt], 0, 0, 0); } } }
.LBB0_2158:
	s_or_b64 exec, exec, s[38:39]
	s_nop 6
	v_cndmask_b32_e64 v32, v32, 0, s[28:29]
	v_cvt_pk_bf16_f32 v32, v32, v65
	ds_write_b16 v140, v32
	v_cndmask_b32_e64 v32, v33, 0, s[30:31]
	v_cvt_pk_bf16_f32 v32, v32, v65
	ds_write_b16 v141, v32
	v_cndmask_b32_e64 v32, v34, 0, s[34:35]
	v_cvt_pk_bf16_f32 v32, v32, v65
	ds_write_b16 v142, v32
	v_cndmask_b32_e64 v32, v35, 0, s[36:37]
	s_ashr_i32 s61, s60, 31
	v_cvt_pk_bf16_f32 v32, v32, v65
	s_lshl_b32 s46, s49, 8
	s_lshl_b64 s[38:39], s[60:61], 1
	v_cmp_gt_u32_e32 vcc, s95, v70
	ds_write_b16 v143, v32
	s_add_u32 s76, s3, s38
	v_cndmask_b32_e32 v32, 0, v70, vcc
	v_add_u32_e32 v34, s46, v128
	s_addc_u32 s77, s78, s39
	v_lshlrev_b32_e32 v64, 1, v32
	v_lshl_add_u64 v[32:33], s[76:77], 0, v[64:65]
	v_mul_u32_u24_e32 v64, 0x8280, v34
	v_lshl_add_u64 v[36:37], v[32:33], 0, v[64:65]
	s_waitcnt lgkmcnt(0)
	s_barrier
	s_waitcnt vmcnt(0)
	v_mov_b32_e32 v32, v194
	v_mov_b32_e32 v33, v195
	v_mov_b32_e32 v34, v196
	v_mov_b32_e32 v35, v197
	v_add_co_u32_e64 v36, s[38:39], s94, v36
	s_waitcnt vmcnt(0)
	v_cndmask_b32_e32 v35, 0, v35, vcc
	v_addc_co_u32_e64 v37, s[38:39], 0, v37, s[38:39]
	v_mov_b32_e32 v48, v198
	v_mov_b32_e32 v49, v199
	v_mov_b32_e32 v50, v200
	v_mov_b32_e32 v51, v201
	v_cndmask_b32_e32 v34, 0, v34, vcc
	v_cndmask_b32_e32 v33, 0, v33, vcc
	v_cndmask_b32_e32 v32, 0, v32, vcc
	ds_read_b128 v[52:55], v166
	ds_read_b128 v[56:59], v166 offset:2304
	ds_read_b128 v[90:93], v166 offset:4608
	ds_read_b128 v[94:97], v166 offset:6912
	s_waitcnt lgkmcnt(3)
	v_mfma_f32_16x16x32_bf16 v[44:47], v[32:35], v[52:55], 0
	s_waitcnt vmcnt(0)
	v_cndmask_b32_e32 v51, 0, v51, vcc
	v_cndmask_b32_e32 v50, 0, v50, vcc
	v_cndmask_b32_e32 v49, 0, v49, vcc
	v_cndmask_b32_e32 v48, 0, v48, vcc
	s_waitcnt lgkmcnt(2)
	v_mfma_f32_16x16x32_bf16 v[40:43], v[32:35], v[56:59], 0
	s_andn2_b64 vcc, exec, s[62:63]
	s_waitcnt lgkmcnt(1)
	v_mfma_f32_16x16x32_bf16 v[36:39], v[32:35], v[90:93], 0
	s_waitcnt lgkmcnt(0)
	v_mfma_f32_16x16x32_bf16 v[32:35], v[32:35], v[94:97], 0
	v_mfma_f32_16x16x32_bf16 v[60:63], v[48:51], v[52:55], 0
	v_mfma_f32_16x16x32_bf16 v[56:59], v[48:51], v[56:59], 0
	v_mfma_f32_16x16x32_bf16 v[52:55], v[48:51], v[90:93], 0
	v_mfma_f32_16x16x32_bf16 v[48:51], v[48:51], v[94:97], 0
	s_cbranch_vccnz .LBB0_2160
	v_cmp_gt_u32_e64 s[38:39], s95, v135
	v_mov_b32_e32 v91, v65
	s_nop 0
	v_cndmask_b32_e64 v89, 0, v135, s[38:39]
	v_lshlrev_b32_e32 v90, 1, v89
	v_lshl_add_u64 v[90:91], s[76:77], 0, v[90:91]
	v_lshl_add_u64 v[94:95], v[90:91], 0, v[64:65]
	v_mov_b32_e32 v90, v202
	v_mov_b32_e32 v91, v203
	v_mov_b32_e32 v92, v204
	v_mov_b32_e32 v93, v205
	v_add_co_u32_e32 v94, vcc, 0x82000, v94
	s_waitcnt vmcnt(0)
	v_cndmask_b32_e64 v93, 0, v93, s[38:39]
	v_addc_co_u32_e32 v95, vcc, 0, v95, vcc
	v_mov_b32_e32 v94, v206
	v_mov_b32_e32 v95, v207
	v_mov_b32_e32 v96, v208
	v_mov_b32_e32 v97, v209
	v_cndmask_b32_e64 v92, 0, v92, s[38:39]
	v_cndmask_b32_e64 v91, 0, v91, s[38:39]
	v_cndmask_b32_e64 v90, 0, v90, s[38:39]
	ds_read_b128 v[98:101], v136
	ds_read_b128 v[174:177], v137
	ds_read_b128 v[178:181], v138
	ds_read_b128 v[182:185], v139
	s_waitcnt lgkmcnt(3)
	v_mfma_f32_16x16x32_bf16 v[44:47], v[90:93], v[98:101], v[44:47]
	s_waitcnt vmcnt(0)
	v_cndmask_b32_e64 v97, 0, v97, s[38:39]
	v_cndmask_b32_e64 v96, 0, v96, s[38:39]
	v_cndmask_b32_e64 v95, 0, v95, s[38:39]
	v_cndmask_b32_e64 v94, 0, v94, s[38:39]
	s_waitcnt lgkmcnt(2)
	v_mfma_f32_16x16x32_bf16 v[40:43], v[90:93], v[174:177], v[40:43]
	s_waitcnt lgkmcnt(1)
	v_mfma_f32_16x16x32_bf16 v[36:39], v[90:93], v[178:181], v[36:39]
	s_waitcnt lgkmcnt(0)
	v_mfma_f32_16x16x32_bf16 v[32:35], v[90:93], v[182:185], v[32:35]
	v_mfma_f32_16x16x32_bf16 v[60:63], v[94:97], v[98:101], v[60:63]
	v_mfma_f32_16x16x32_bf16 v[56:59], v[94:97], v[174:177], v[56:59]
	v_mfma_f32_16x16x32_bf16 v[52:55], v[94:97], v[178:181], v[52:55]
	v_mfma_f32_16x16x32_bf16 v[48:51], v[94:97], v[182:185], v[48:51]

; __device__ __forceinline__ unsigned cvt_pk_bf16(float lo, float hi) { unsigned r; asm volatile("v_cvt_pk_bf16_f32 %0, %1, %2" : "=v"(r) : "v"(lo), "v"(hi)); return r; }
; __device__ __forceinline__ float bf_lo(unsigned w) { return __uint_as_float(w << 16); }
; __device__ __forceinline__ float bf_hi(unsigned w) { return __uint_as_float(w & 0xffff0000u); }
; __device__ __forceinline__ float siluf_(float x) { return x * sigmoidf_(x); }
; __device__ __forceinline__ void gla_g3(const Params& P, unsigned char* lds) {
;     ...
; #pragma unroll
;         for (int lt = 0; lt < 4; ++lt)
; #pragma unroll
;             for (int nt = 0; nt < 2; ++nt) { const int l = 16 * lt + fr, lc = l < I.L ? l : I.L - 1;
;                 gwp[lt][nt] = *(const u32x2*)(gg + (size_t)(I.row0 + lc) * D + I.h * DV + 32 * wid + 16 * nt + 4 * fq); }
;         __syncthreads();
; #pragma unroll
;         for (int lt = 0; lt < 4; ++lt) { const int l = 16 * lt + fr;
;             if (l < I.L) { float tot = 0.f;
; #pragma unroll
;                 for (int w8 = 0; w8 < 8; ++w8) tot += ssh[w8 * 64 + l];
;                 const float ro = rsqrtf(tot * (1.0f / 256.0f) + EPS);
; #pragma unroll
;                 for (int nt = 0; nt < 2; ++nt) { const int dvh = 32 * wid + 16 * nt + 4 * fq; const size_t off = (size_t)(I.row0 + l) * D + I.h * DV + dvh;
;                     const u32x2 gw = gwp[lt][nt]; const f32x4 nw = *(const f32x4*)(P.in[16] + dvh);
;                     const float o0 = acc[nt][lt][0] * ro * nw[0] * siluf_(bf_lo(gw.x)), o1 = acc[nt][lt][1] * ro * nw[1] * siluf_(bf_hi(gw.x));
;                     const float o2 = acc[nt][lt][2] * ro * nw[2] * siluf_(bf_lo(gw.y)), o3 = acc[nt][lt][3] * ro * nw[3] * siluf_(bf_hi(gw.y));
;                     u32x2 w; w.x = cvt_pk_bf16(o0, o1); w.y = cvt_pk_bf16(o2, o3); *(u32x2*)(og + off) = w; } } }
.LBB0_2170:
	s_or_b64 exec, exec, s[62:63]
	v_min_i32_e32 v64, s64, v103
	v_add_u32_e32 v92, s60, v64
	v_min_i32_e32 v64, s64, v132
	s_lshl_b32 s46, s46, 1
	v_ashrrev_i32_e32 v93, 31, v92
	v_add_u32_e32 v94, s60, v64
	v_lshl_add_u64 v[90:91], v[74:75], 0, s[46:47]
	v_lshlrev_b64 v[92:93], 11, v[92:93]
	v_ashrrev_i32_e32 v95, 31, v94
	v_lshl_add_u64 v[92:93], v[90:91], 0, v[92:93]
	v_lshlrev_b64 v[94:95], 11, v[94:95]
	v_min_i32_e32 v64, s64, v133
	v_lshl_add_u64 v[94:95], v[90:91], 0, v[94:95]
	global_load_dwordx2 v[178:179], v[92:93], off
	global_load_dwordx2 v[180:181], v[92:93], off offset:32
	global_load_dwordx2 v[100:101], v[94:95], off
	global_load_dwordx2 v[98:99], v[94:95], off offset:32
	v_add_u32_e32 v92, s60, v64
	v_min_i32_e32 v64, s64, v134
	v_add_u32_e32 v94, s60, v64
	v_ashrrev_i32_e32 v93, 31, v92
	v_ashrrev_i32_e32 v95, 31, v94
	v_lshlrev_b64 v[92:93], 11, v[92:93]
	v_lshlrev_b64 v[94:95], 11, v[94:95]
	v_lshl_add_u64 v[92:93], v[90:91], 0, v[92:93]
	v_lshl_add_u64 v[90:91], v[90:91], 0, v[94:95]
	global_load_dwordx2 v[96:97], v[92:93], off
	global_load_dwordx2 v[94:95], v[92:93], off offset:32
	s_nop 0
	global_load_dwordx2 v[92:93], v[90:91], off
	s_nop 0
	global_load_dwordx2 v[90:91], v[90:91], off offset:32
	s_waitcnt lgkmcnt(0)
	s_barrier
	s_nop 0
	v_mov_b32_e32 v174, v212
	v_mov_b32_e32 v175, v213
	v_mov_b32_e32 v176, v214
	v_mov_b32_e32 v177, v215
	ds_read2st64_b32 v[184:185], v104 offset1:1
	ds_read2st64_b32 v[186:187], v104 offset0:2 offset1:3
	ds_read2st64_b32 v[188:189], v104 offset0:4 offset1:5
	ds_read2st64_b32 v[190:191], v104 offset0:6 offset1:7
	v_add_u32_e32 v182, s60, v103
	s_add_u32 s62, s79, s46
	v_ashrrev_i32_e32 v183, 31, v182
	s_waitcnt lgkmcnt(3)
	v_add_f32_e32 v64, 0, v184
	v_add_f32_e32 v64, v64, v185
	s_waitcnt lgkmcnt(2)
	v_add_f32_e32 v64, v64, v186
	v_add_f32_e32 v64, v64, v187
	s_waitcnt lgkmcnt(1)
	v_add_f32_e32 v64, v64, v188
	v_add_f32_e32 v64, v64, v189
	s_waitcnt lgkmcnt(0)
	v_add_f32_e32 v64, v64, v190
	v_add_f32_e32 v64, v64, v191
	v_fmamk_f32 v64, v64, 0x3b800000, v169
	v_mul_f32_e32 v173, 0x4b800000, v64
	v_cmp_gt_f32_e32 vcc, s90, v64
	s_addc_u32 s63, s80, 0
	v_lshlrev_b64 v[182:183], 11, v[182:183]
	v_cndmask_b32_e32 v64, v64, v173, vcc
	v_rsq_f32_e32 v64, v64
	v_mov_b32_e32 v89, v65
	v_lshl_add_u64 v[182:183], s[62:63], 0, v[182:183]
	v_lshl_add_u64 v[182:183], v[182:183], 0, v[88:89]
	v_mul_f32_e32 v173, 0x45800000, v64
	v_cndmask_b32_e32 v64, v64, v173, vcc
	v_mul_f32_e32 v185, v60, v64
	v_mul_f32_e32 v187, v62, v64
	v_mul_f32_e32 v61, v61, v64
	v_mul_f32_e32 v63, v63, v64
	v_mul_f32_e32 v57, v57, v64
	v_mul_f32_e32 v59, v59, v64
	v_cmp_gt_u32_e32 vcc, s95, v132
	s_waitcnt vmcnt(7)
	v_and_b32_e32 v60, 0xffff0000, v178
	v_lshlrev_b32_e32 v186, 16, v179
	v_lshlrev_b32_e32 v184, 16, v178
	v_and_b32_e32 v62, 0xffff0000, v179
	v_mul_f32_e32 v173, 0xbfb8aa3b, v184
	v_mul_f32_e32 v178, 0xbfb8aa3b, v62
	v_exp_f32_e32 v173, v173
	v_exp_f32_e32 v178, v178
	v_add_f32_e32 v173, 1.0, v173
	v_add_f32_e32 v178, 1.0, v178
	v_rcp_f32_e32 v188, v173
	s_waitcnt vmcnt(0)
	v_mov_b32_e32 v189, v174
	v_mov_b32_e32 v191, v176
	v_mul_f32_e32 v174, 0xbfb8aa3b, v60
	v_mul_f32_e32 v176, 0xbfb8aa3b, v186
	v_exp_f32_e32 v174, v174
	v_exp_f32_e32 v176, v176
	v_add_f32_e32 v174, 1.0, v174
	v_add_f32_e32 v176, 1.0, v176
	v_rcp_f32_e32 v174, v174
	v_rcp_f32_e32 v190, v176
	v_rcp_f32_e32 v176, v178
	v_pk_mul_f32 v[178:179], v[188:189], v[184:185]
	v_pk_mul_f32 v[60:61], v[174:175], v[60:61]
	v_pk_mul_f32 v[174:175], v[190:191], v[186:187]
	v_pk_mul_f32 v[62:63], v[176:177], v[62:63]
	v_mul_f32_e32 v60, v60, v61
	v_mul_f32_e32 v61, v174, v175
	v_mul_f32_e32 v173, v178, v179
	v_mul_f32_e32 v62, v62, v63
	v_cvt_pk_bf16_f32 v60, v173, v60
	v_cvt_pk_bf16_f32 v61, v61, v62
	global_store_dwordx2 v[182:183], v[60:61], off
	s_nop 0
	v_mov_b32_e32 v60, v216
	v_mov_b32_e32 v61, v217
	v_mov_b32_e32 v62, v218
	v_mov_b32_e32 v63, v219
	v_mul_f32_e32 v175, v56, v64
	v_mul_f32_e32 v177, v58, v64
	v_and_b32_e32 v56, 0xffff0000, v180
	v_and_b32_e32 v58, 0xffff0000, v181
	v_lshlrev_b32_e32 v174, 16, v180
	v_lshlrev_b32_e32 v176, 16, v181
	v_mul_f32_e32 v173, 0xbfb8aa3b, v56
	v_mul_f32_e32 v179, 0xbfb8aa3b, v58
	v_mul_f32_e32 v64, 0xbfb8aa3b, v174
	v_mul_f32_e32 v178, 0xbfb8aa3b, v176
	v_exp_f32_e32 v173, v173
	v_exp_f32_e32 v179, v179
	v_exp_f32_e32 v64, v64
	v_exp_f32_e32 v178, v178
	v_add_f32_e32 v173, 1.0, v173
	v_add_f32_e32 v184, 1.0, v179
	v_add_f32_e32 v64, 1.0, v64
	v_add_f32_e32 v180, 1.0, v178
	v_rcp_f32_e32 v178, v64
	v_rcp_f32_e32 v180, v180
	s_nop 0
	v_mov_b32_e32 v179, v60
	v_rcp_f32_e32 v60, v173
	v_mov_b32_e32 v181, v62
	v_rcp_f32_e32 v62, v184
	v_pk_mul_f32 v[174:175], v[178:179], v[174:175]
	v_pk_mul_f32 v[56:57], v[60:61], v[56:57]
	v_pk_mul_f32 v[176:177], v[180:181], v[176:177]
	v_pk_mul_f32 v[58:59], v[62:63], v[58:59]
	v_mul_f32_e32 v56, v56, v57
	v_mul_f32_e32 v57, v58, v59
	v_mul_f32_e32 v64, v174, v175
	v_mul_f32_e32 v173, v176, v177
	v_cvt_pk_bf16_f32 v56, v64, v56
	v_cvt_pk_bf16_f32 v57, v173, v57
	global_store_dwordx2 v[182:183], v[56:57], off offset:32
	s_and_saveexec_b64 s[76:77], vcc
	s_cbranch_execz .LBB0_2177
; __device__ __forceinline__ unsigned cvt_pk_bf16(float lo, float hi) { unsigned r; asm volatile("v_cvt_pk_bf16_f32 %0, %1, %2" : "=v"(r) : "v"(lo), "v"(hi)); return r; }
; __device__ __forceinline__ float bf_lo(unsigned w) { return __uint_as_float(w << 16); }
; __device__ __forceinline__ float bf_hi(unsigned w) { return __uint_as_float(w & 0xffff0000u); }
; __device__ __forceinline__ float siluf_(float x) { return x * sigmoidf_(x); }
; __device__ __forceinline__ void gla_g3(const Params& P, unsigned char* lds) {
;     ...
;         for (int lt = 0; lt < 4; ++lt) { const int l = 16 * lt + fr;
;             if (l < I.L) { float tot = 0.f;
; #pragma unroll
;                 for (int w8 = 0; w8 < 8; ++w8) tot += ssh[w8 * 64 + l];
;                 const float ro = rsqrtf(tot * (1.0f / 256.0f) + EPS);
; #pragma unroll
;                 for (int nt = 0; nt < 2; ++nt) { const int dvh = 32 * wid + 16 * nt + 4 * fq; const size_t off = (size_t)(I.row0 + l) * D + I.h * DV + dvh;
;                     const u32x2 gw = gwp[lt][nt]; const f32x4 nw = *(const f32x4*)(P.in[16] + dvh);
;                     const float o0 = acc[nt][lt][0] * ro * nw[0] * siluf_(bf_lo(gw.x)), o1 = acc[nt][lt][1] * ro * nw[1] * siluf_(bf_hi(gw.x));
;                     const float o2 = acc[nt][lt][2] * ro * nw[2] * siluf_(bf_lo(gw.y)), o3 = acc[nt][lt][3] * ro * nw[3] * siluf_(bf_hi(gw.y));
;                     u32x2 w; w.x = cvt_pk_bf16(o0, o1); w.y = cvt_pk_bf16(o2, o3); *(u32x2*)(og + off) = w; } } }
	s_nop 0
	v_mov_b32_e32 v56, v212
	v_mov_b32_e32 v57, v213
	v_mov_b32_e32 v58, v214
	v_mov_b32_e32 v59, v215
	ds_read2st64_b32 v[60:61], v144 offset1:1
	ds_read2st64_b32 v[62:63], v144 offset0:2 offset1:3
	ds_read2st64_b32 v[174:175], v144 offset0:4 offset1:5
	ds_read2st64_b32 v[176:177], v144 offset0:6 offset1:7
	v_lshlrev_b32_e32 v180, 16, v100
	s_waitcnt lgkmcnt(3)
	v_add_f32_e32 v60, 0, v60
	v_add_f32_e32 v60, v60, v61
	s_waitcnt lgkmcnt(2)
	v_add_f32_e32 v60, v60, v62
	v_add_f32_e32 v60, v60, v63
	s_waitcnt lgkmcnt(1)
	v_add_f32_e32 v60, v60, v174
	v_add_f32_e32 v60, v60, v175
	s_waitcnt lgkmcnt(0)
	v_add_f32_e32 v60, v60, v176
	v_add_f32_e32 v60, v60, v177
	v_lshlrev_b32_e32 v182, 16, v101
	v_fmamk_f32 v60, v60, 0x3b800000, v169
	v_and_b32_e32 v100, 0xffff0000, v100
	v_and_b32_e32 v184, 0xffff0000, v101
	v_mul_f32_e32 v64, 0xbfb8aa3b, v180
	v_mul_f32_e32 v173, 0xbfb8aa3b, v182
	v_mul_f32_e32 v62, 0x4b800000, v60
	v_cmp_gt_f32_e32 vcc, s90, v60
	v_add_u32_e32 v178, s60, v132
	v_mul_f32_e32 v101, 0xbfb8aa3b, v100
	v_mul_f32_e32 v181, 0xbfb8aa3b, v184
	v_exp_f32_e32 v64, v64
	v_exp_f32_e32 v173, v173
	v_cndmask_b32_e32 v60, v60, v62, vcc
	v_ashrrev_i32_e32 v179, 31, v178
	v_exp_f32_e32 v101, v101
	v_exp_f32_e32 v181, v181
	v_rsq_f32_e32 v63, v60
	v_lshlrev_b64 v[178:179], 11, v[178:179]
	v_lshl_add_u64 v[178:179], s[62:63], 0, v[178:179]
	v_lshl_add_u64 v[178:179], v[178:179], 0, v[88:89]
	v_add_f32_e32 v61, 1.0, v64
	v_add_f32_e32 v89, 1.0, v173
	v_add_f32_e32 v64, 1.0, v101
	v_add_f32_e32 v173, 1.0, v181
	v_rcp_f32_e32 v60, v61
	v_rcp_f32_e32 v62, v89
	v_mul_f32_e32 v61, 0x45800000, v63
	v_cndmask_b32_e32 v89, v63, v61, vcc
	v_mul_f32_e32 v181, v52, v89
	v_mul_f32_e32 v183, v54, v89
	v_mul_f32_e32 v101, v53, v89
	v_mul_f32_e32 v185, v55, v89
	s_nop 0
	v_mov_b32_e32 v61, v56
	v_rcp_f32_e32 v56, v64
	v_mov_b32_e32 v63, v58
	v_rcp_f32_e32 v58, v173
	v_pk_mul_f32 v[52:53], v[60:61], v[180:181]
	v_pk_mul_f32 v[54:55], v[62:63], v[182:183]
	v_mul_f32_e32 v60, v52, v53
	v_mul_f32_e32 v61, v54, v55
	v_pk_mul_f32 v[52:53], v[56:57], v[100:101]
	v_pk_mul_f32 v[54:55], v[58:59], v[184:185]
	v_mul_f32_e32 v52, v52, v53
	v_mul_f32_e32 v53, v54, v55
	v_cvt_pk_bf16_f32 v52, v60, v52
	v_cvt_pk_bf16_f32 v53, v61, v53
	global_store_dwordx2 v[178:179], v[52:53], off
	s_nop 0
	v_mov_b32_e32 v52, v216
	v_mov_b32_e32 v53, v217
	v_mov_b32_e32 v54, v218
	v_mov_b32_e32 v55, v219
	v_lshlrev_b32_e32 v56, 16, v98
	v_and_b32_e32 v58, 0xffff0000, v98
	v_lshlrev_b32_e32 v60, 16, v99
	v_and_b32_e32 v62, 0xffff0000, v99
	v_mul_f32_e32 v57, 0xbfb8aa3b, v56
	v_mul_f32_e32 v59, 0xbfb8aa3b, v58
	v_mul_f32_e32 v61, 0xbfb8aa3b, v60
	v_mul_f32_e32 v63, 0xbfb8aa3b, v62
	v_exp_f32_e32 v57, v57
	v_exp_f32_e32 v59, v59
	v_exp_f32_e32 v61, v61
	v_exp_f32_e32 v63, v63
	v_add_f32_e32 v57, 1.0, v57
	v_add_f32_e32 v64, 1.0, v59
	v_add_f32_e32 v59, 1.0, v61
	v_add_f32_e32 v173, 1.0, v63
	v_rcp_f32_e32 v98, v57
	v_rcp_f32_e32 v100, v59
	v_mul_f32_e32 v57, v48, v89
	v_mul_f32_e32 v61, v50, v89
	v_mul_f32_e32 v59, v49, v89
	v_mul_f32_e32 v63, v51, v89
	s_nop 0
	v_mov_b32_e32 v99, v52
	v_rcp_f32_e32 v52, v64
	v_mov_b32_e32 v101, v54
	v_rcp_f32_e32 v54, v173
	v_pk_mul_f32 v[48:49], v[98:99], v[56:57]
	v_pk_mul_f32 v[50:51], v[100:101], v[60:61]
	v_mul_f32_e32 v56, v48, v49
	v_mul_f32_e32 v57, v50, v51
	v_pk_mul_f32 v[48:49], v[52:53], v[58:59]
	v_pk_mul_f32 v[50:51], v[54:55], v[62:63]
	v_mul_f32_e32 v48, v48, v49
	v_mul_f32_e32 v49, v50, v51
	v_cvt_pk_bf16_f32 v48, v56, v48
	v_cvt_pk_bf16_f32 v49, v57, v49
	global_store_dwordx2 v[178:179], v[48:49], off offset:32
	s_or_b64 exec, exec, s[76:77]
	v_cmp_gt_u32_e32 vcc, s95, v133
	s_and_saveexec_b64 s[76:77], vcc
	s_cbranch_execnz .LBB0_2178

; __device__ __forceinline__ void gla_g3(const Params& P, unsigned char* lds) {
;     ...
;         for (int s = 0; s < 2; ++s) { const int t8 = 32 * s + 8 * fq;
;             if (32 * s < I.L) {
;                 bf16x8 vf[2];
; #pragma unroll
;                 for (int nt = 0; nt < 2; ++nt) { const int tc = t8 < I.L ? t8 : 0; vf[nt] = *(const bf16x8*)(vT + (size_t)(I.h * DV + 32 * wid + 16 * nt + fr) * MPAD + I.row0 + tc); if (t8 >= I.L) vf[nt] = (bf16x8){0, 0, 0, 0, 0, 0, 0, 0}; }
.Lg3_loadb:
	s_and_b32 s49, s46, 3
	s_lshl_b32 s46, s49, 8
	s_lshl_b32 s98, s49, 9
	s_add_u32 s100, s54, 0x308dc00
	s_addc_u32 s101, s55, 0
	v_lshrrev_b32_e32 v48, 3, v210
	v_add_u32_e32 v48, s60, v48
	v_lshlrev_b32_e32 v48, 11, v48
	v_and_b32_e32 v49, 7, v210
	v_lshl_add_u32 v49, v49, 6, s98
	v_add_u32_e32 v48, v48, v49
	v_lshlrev_b32_e32 v49, 6, v210
	v_add_u32_e32 v49, 0x1000, v49
	v_lshlrev_b32_e64 v220, 1, s60
	v_add_u32_e32 v223, s46, v128
	v_mul_u32_u24_e32 v223, 0x8280, v223
	v_cmp_gt_u32_e32 vcc, s95, v70
	s_nop 1
	v_cndmask_b32_e32 v222, 0, v70, vcc
	v_lshl_add_u32 v222, v222, 1, v220
	v_add_u32_e32 v222, v222, v223
	v_mov_b32_e32 v225, s78
	v_add_co_u32_e32 v224, vcc, s3, v222
	v_addc_co_u32_e32 v225, vcc, 0, v225, vcc
	global_load_dwordx4 v[194:197], v[224:225], off
	v_add_co_u32_e32 v226, vcc, 0x82800, v224
	v_addc_co_u32_e32 v227, vcc, 0, v225, vcc
	global_load_dwordx4 v[198:201], v[226:227], off
	v_cmp_gt_u32_e32 vcc, s95, v135
	s_nop 1
	v_cndmask_b32_e32 v222, 0, v135, vcc
	v_lshl_add_u32 v222, v222, 1, v220
	v_add_u32_e32 v222, v222, v223
	v_mov_b32_e32 v225, s78
	v_add_co_u32_e32 v224, vcc, s3, v222
	v_addc_co_u32_e32 v225, vcc, 0, v225, vcc
	global_load_dwordx4 v[202:205], v[224:225], off
	v_add_co_u32_e32 v226, vcc, 0x82800, v224
	v_addc_co_u32_e32 v227, vcc, 0, v225, vcc
	global_load_dwordx4 v[206:209], v[226:227], off
	s_mov_b64 s[98:99], exec
	s_cmp_eq_u32 s95, 64
	s_cbranch_scc1 .Lg3_ball
	v_cmp_gt_u32_e32 vcc, 0x80, v210
	s_nop 1
	s_and_b64 exec, exec, vcc
	s_cbranch_execz .Lg3_bskip

; __device__ __forceinline__ unsigned cvt_pk_bf16(float lo, float hi) { unsigned r; asm volatile("v_cvt_pk_bf16_f32 %0, %1, %2" : "=v"(r) : "v"(lo), "v"(hi)); return r; }
; __device__ __forceinline__ float bf_lo(unsigned w) { return __uint_as_float(w << 16); }
; __device__ __forceinline__ float bf_hi(unsigned w) { return __uint_as_float(w & 0xffff0000u); }
; __device__ __forceinline__ float siluf_(float x) { return x * sigmoidf_(x); }
; __device__ __forceinline__ void gla_g3(const Params& P, unsigned char* lds) {
;     ...
;         for (int lt = 0; lt < 4; ++lt) { const int l = 16 * lt + fr;
;             if (l < I.L) { float tot = 0.f;
; #pragma unroll
;                 for (int w8 = 0; w8 < 8; ++w8) tot += ssh[w8 * 64 + l];
;                 const float ro = rsqrtf(tot * (1.0f / 256.0f) + EPS);
; #pragma unroll
;                 for (int nt = 0; nt < 2; ++nt) { const int dvh = 32 * wid + 16 * nt + 4 * fq; const size_t off = (size_t)(I.row0 + l) * D + I.h * DV + dvh;
;                     const u32x2 gw = gwp[lt][nt]; const f32x4 nw = *(const f32x4*)(P.in[16] + dvh);
;                     const float o0 = acc[nt][lt][0] * ro * nw[0] * siluf_(bf_lo(gw.x)), o1 = acc[nt][lt][1] * ro * nw[1] * siluf_(bf_hi(gw.x));
;                     const float o2 = acc[nt][lt][2] * ro * nw[2] * siluf_(bf_lo(gw.y)), o3 = acc[nt][lt][3] * ro * nw[3] * siluf_(bf_hi(gw.y));
;                     u32x2 w; w.x = cvt_pk_bf16(o0, o1); w.y = cvt_pk_bf16(o2, o3); *(u32x2*)(og + off) = w; } } }
.LBB0_2178:
	s_nop 0
	v_mov_b32_e32 v48, v212
	v_mov_b32_e32 v49, v213
	v_mov_b32_e32 v50, v214
	v_mov_b32_e32 v51, v215
	ds_read2st64_b32 v[52:53], v145 offset1:1
	ds_read2st64_b32 v[54:55], v145 offset0:2 offset1:3
	ds_read2st64_b32 v[56:57], v145 offset0:4 offset1:5
	ds_read2st64_b32 v[58:59], v145 offset0:6 offset1:7
	v_lshlrev_b32_e32 v62, 16, v96
	s_waitcnt lgkmcnt(3)
	v_add_f32_e32 v52, 0, v52
	v_add_f32_e32 v52, v52, v53
	s_waitcnt lgkmcnt(2)
	v_add_f32_e32 v52, v52, v54
	v_add_f32_e32 v52, v52, v55
	s_waitcnt lgkmcnt(1)
	v_add_f32_e32 v52, v52, v56
	v_add_f32_e32 v52, v52, v57
	s_waitcnt lgkmcnt(0)
	v_add_f32_e32 v52, v52, v58
	v_add_f32_e32 v52, v52, v59
	v_lshlrev_b32_e32 v98, 16, v97
	v_fmamk_f32 v52, v52, 0x3b800000, v169
	v_and_b32_e32 v96, 0xffff0000, v96
	v_and_b32_e32 v100, 0xffff0000, v97
	v_mul_f32_e32 v63, 0xbfb8aa3b, v62
	v_mul_f32_e32 v97, 0xbfb8aa3b, v98
	v_mul_f32_e32 v54, 0x4b800000, v52
	v_cmp_gt_f32_e32 vcc, s90, v52
	v_mul_f32_e32 v64, 0xbfb8aa3b, v96
	v_mul_f32_e32 v99, 0xbfb8aa3b, v100
	v_exp_f32_e32 v63, v63
	v_exp_f32_e32 v97, v97
	v_cndmask_b32_e32 v52, v52, v54, vcc
	v_exp_f32_e32 v64, v64
	v_exp_f32_e32 v99, v99
	v_rsq_f32_e32 v55, v52
	v_add_f32_e32 v53, 1.0, v63
	v_add_f32_e32 v63, 1.0, v97
	v_add_f32_e32 v64, 1.0, v64
	v_add_f32_e32 v56, 1.0, v99
	v_rcp_f32_e32 v52, v53
	v_rcp_f32_e32 v54, v63
	v_mul_f32_e32 v53, 0x45800000, v55
	v_cndmask_b32_e32 v57, v55, v53, vcc
	v_add_u32_e32 v60, s60, v133
	v_ashrrev_i32_e32 v61, 31, v60
	v_mul_f32_e32 v63, v44, v57
	v_mul_f32_e32 v99, v46, v57
	v_lshlrev_b64 v[60:61], 11, v[60:61]
	v_mul_f32_e32 v97, v45, v57
	v_mul_f32_e32 v101, v47, v57
	v_mov_b32_e32 v89, v65
	v_lshl_add_u64 v[60:61], s[62:63], 0, v[60:61]
	v_lshl_add_u64 v[60:61], v[60:61], 0, v[88:89]
	s_nop 0
	v_mov_b32_e32 v53, v48
	v_rcp_f32_e32 v48, v64
	v_mov_b32_e32 v55, v50
	v_rcp_f32_e32 v50, v56
	v_pk_mul_f32 v[44:45], v[52:53], v[62:63]
	v_pk_mul_f32 v[46:47], v[54:55], v[98:99]
	v_mul_f32_e32 v52, v44, v45
	v_mul_f32_e32 v53, v46, v47
	v_pk_mul_f32 v[44:45], v[48:49], v[96:97]
	v_pk_mul_f32 v[46:47], v[50:51], v[100:101]
	v_mul_f32_e32 v44, v44, v45
	v_mul_f32_e32 v45, v46, v47
	v_cvt_pk_bf16_f32 v44, v52, v44
	v_cvt_pk_bf16_f32 v45, v53, v45
	global_store_dwordx2 v[60:61], v[44:45], off
	s_nop 0
	v_mov_b32_e32 v44, v216
	v_mov_b32_e32 v45, v217
	v_mov_b32_e32 v46, v218
	v_mov_b32_e32 v47, v219
	v_lshlrev_b32_e32 v48, 16, v94
	v_and_b32_e32 v50, 0xffff0000, v94
	v_lshlrev_b32_e32 v52, 16, v95
	v_and_b32_e32 v54, 0xffff0000, v95
	v_mul_f32_e32 v49, 0xbfb8aa3b, v48
	v_mul_f32_e32 v51, 0xbfb8aa3b, v50
	v_mul_f32_e32 v53, 0xbfb8aa3b, v52
	v_mul_f32_e32 v55, 0xbfb8aa3b, v54
	v_exp_f32_e32 v49, v49
	v_exp_f32_e32 v51, v51
	v_exp_f32_e32 v53, v53
	v_exp_f32_e32 v55, v55
	v_add_f32_e32 v49, 1.0, v49
	v_add_f32_e32 v59, 1.0, v51
	v_add_f32_e32 v51, 1.0, v53
	v_add_f32_e32 v62, 1.0, v55
	v_rcp_f32_e32 v56, v49
	v_rcp_f32_e32 v58, v51
	v_mul_f32_e32 v49, v40, v57
	v_mul_f32_e32 v51, v41, v57
	v_mul_f32_e32 v53, v42, v57
	v_mul_f32_e32 v55, v43, v57
	s_nop 0
	v_mov_b32_e32 v57, v44
	v_rcp_f32_e32 v44, v59
	v_mov_b32_e32 v59, v46
	v_rcp_f32_e32 v46, v62
	v_pk_mul_f32 v[40:41], v[56:57], v[48:49]
	v_pk_mul_f32 v[42:43], v[58:59], v[52:53]
	v_mul_f32_e32 v48, v40, v41
	v_mul_f32_e32 v49, v42, v43
	v_pk_mul_f32 v[40:41], v[44:45], v[50:51]
	v_pk_mul_f32 v[42:43], v[46:47], v[54:55]
	v_mul_f32_e32 v40, v40, v41
	v_mul_f32_e32 v41, v42, v43
	v_cvt_pk_bf16_f32 v40, v48, v40
	v_cvt_pk_bf16_f32 v41, v49, v41
	global_store_dwordx2 v[60:61], v[40:41], off offset:32
	s_or_b64 exec, exec, s[76:77]
	v_cmp_gt_u32_e32 vcc, s95, v134
	s_and_saveexec_b64 s[76:77], vcc
	s_cbranch_execz .LBB0_2141
; __device__ __forceinline__ unsigned cvt_pk_bf16(float lo, float hi) { unsigned r; asm volatile("v_cvt_pk_bf16_f32 %0, %1, %2" : "=v"(r) : "v"(lo), "v"(hi)); return r; }
; __device__ __forceinline__ float bf_lo(unsigned w) { return __uint_as_float(w << 16); }
; __device__ __forceinline__ float bf_hi(unsigned w) { return __uint_as_float(w & 0xffff0000u); }
; __device__ __forceinline__ float siluf_(float x) { return x * sigmoidf_(x); }
; __device__ __forceinline__ void gla_g3(const Params& P, unsigned char* lds) {
;     ...
;         for (int lt = 0; lt < 4; ++lt) { const int l = 16 * lt + fr;
;             if (l < I.L) { float tot = 0.f;
; #pragma unroll
;                 for (int w8 = 0; w8 < 8; ++w8) tot += ssh[w8 * 64 + l];
;                 const float ro = rsqrtf(tot * (1.0f / 256.0f) + EPS);
; #pragma unroll
;                 for (int nt = 0; nt < 2; ++nt) { const int dvh = 32 * wid + 16 * nt + 4 * fq; const size_t off = (size_t)(I.row0 + l) * D + I.h * DV + dvh;
;                     const u32x2 gw = gwp[lt][nt]; const f32x4 nw = *(const f32x4*)(P.in[16] + dvh);
;                     const float o0 = acc[nt][lt][0] * ro * nw[0] * siluf_(bf_lo(gw.x)), o1 = acc[nt][lt][1] * ro * nw[1] * siluf_(bf_hi(gw.x));
;                     const float o2 = acc[nt][lt][2] * ro * nw[2] * siluf_(bf_lo(gw.y)), o3 = acc[nt][lt][3] * ro * nw[3] * siluf_(bf_hi(gw.y));
;                     u32x2 w; w.x = cvt_pk_bf16(o0, o1); w.y = cvt_pk_bf16(o2, o3); *(u32x2*)(og + off) = w; } } }
.LBB0_2179:
	s_nop 0
	v_mov_b32_e32 v40, v212
	v_mov_b32_e32 v41, v213
	v_mov_b32_e32 v42, v214
	v_mov_b32_e32 v43, v215
	ds_read2st64_b32 v[44:45], v146 offset1:1
	ds_read2st64_b32 v[46:47], v146 offset0:2 offset1:3
	ds_read2st64_b32 v[48:49], v146 offset0:4 offset1:5
	ds_read2st64_b32 v[50:51], v146 offset0:6 offset1:7
	v_lshlrev_b32_e32 v54, 16, v92
	s_waitcnt lgkmcnt(3)
	v_add_f32_e32 v44, 0, v44
	v_add_f32_e32 v44, v44, v45
	s_waitcnt lgkmcnt(2)
	v_add_f32_e32 v44, v44, v46
	v_add_f32_e32 v44, v44, v47
	s_waitcnt lgkmcnt(1)
	v_add_f32_e32 v44, v44, v48
	v_add_f32_e32 v44, v44, v49
	s_waitcnt lgkmcnt(0)
	v_add_f32_e32 v44, v44, v50
	v_add_f32_e32 v44, v44, v51
	v_lshlrev_b32_e32 v58, 16, v93
	v_fmamk_f32 v44, v44, 0x3b800000, v169
	v_and_b32_e32 v56, 0xffff0000, v92
	v_and_b32_e32 v60, 0xffff0000, v93
	v_mul_f32_e32 v55, 0xbfb8aa3b, v54
	v_mul_f32_e32 v59, 0xbfb8aa3b, v58
	v_mul_f32_e32 v46, 0x4b800000, v44
	v_cmp_gt_f32_e32 vcc, s90, v44
	v_mul_f32_e32 v57, 0xbfb8aa3b, v56
	v_mul_f32_e32 v61, 0xbfb8aa3b, v60
	v_exp_f32_e32 v55, v55
	v_exp_f32_e32 v59, v59
	v_cndmask_b32_e32 v44, v44, v46, vcc
	v_exp_f32_e32 v57, v57
	v_exp_f32_e32 v61, v61
	v_rsq_f32_e32 v47, v44
	v_add_f32_e32 v45, 1.0, v55
	v_add_f32_e32 v55, 1.0, v59
	v_add_f32_e32 v62, 1.0, v57
	v_add_f32_e32 v48, 1.0, v61
	v_rcp_f32_e32 v44, v45
	v_rcp_f32_e32 v46, v55
	v_mul_f32_e32 v45, 0x45800000, v47
	v_cndmask_b32_e32 v49, v47, v45, vcc
	v_add_u32_e32 v52, s60, v134
	v_ashrrev_i32_e32 v53, 31, v52
	v_mul_f32_e32 v55, v36, v49
	v_mul_f32_e32 v59, v38, v49
	v_lshlrev_b64 v[52:53], 11, v[52:53]
	v_mul_f32_e32 v57, v37, v49
	v_mul_f32_e32 v61, v39, v49
	v_mov_b32_e32 v89, v65
	v_lshl_add_u64 v[52:53], s[62:63], 0, v[52:53]
	v_lshl_add_u64 v[52:53], v[52:53], 0, v[88:89]
	s_nop 0
	v_mov_b32_e32 v45, v40
	v_rcp_f32_e32 v40, v62
	v_mov_b32_e32 v47, v42
	v_rcp_f32_e32 v42, v48
	v_pk_mul_f32 v[36:37], v[44:45], v[54:55]
	v_pk_mul_f32 v[38:39], v[46:47], v[58:59]
	v_mul_f32_e32 v44, v36, v37
	v_mul_f32_e32 v45, v38, v39
	v_pk_mul_f32 v[36:37], v[40:41], v[56:57]
	v_pk_mul_f32 v[38:39], v[42:43], v[60:61]
	v_mul_f32_e32 v36, v36, v37
	v_mul_f32_e32 v37, v38, v39
	v_cvt_pk_bf16_f32 v36, v44, v36
	v_cvt_pk_bf16_f32 v37, v45, v37
	global_store_dwordx2 v[52:53], v[36:37], off
	s_nop 0
	v_mov_b32_e32 v36, v216
	v_mov_b32_e32 v37, v217
	v_mov_b32_e32 v38, v218
	v_mov_b32_e32 v39, v219
	v_lshlrev_b32_e32 v40, 16, v90
	v_and_b32_e32 v42, 0xffff0000, v90
	v_lshlrev_b32_e32 v44, 16, v91
	v_and_b32_e32 v46, 0xffff0000, v91
	v_mul_f32_e32 v41, 0xbfb8aa3b, v40
	v_mul_f32_e32 v43, 0xbfb8aa3b, v42
	v_mul_f32_e32 v45, 0xbfb8aa3b, v44
	v_mul_f32_e32 v47, 0xbfb8aa3b, v46
	v_exp_f32_e32 v41, v41
	v_exp_f32_e32 v43, v43
	v_exp_f32_e32 v45, v45
	v_exp_f32_e32 v47, v47
	v_add_f32_e32 v41, 1.0, v41
	v_add_f32_e32 v51, 1.0, v43
	v_add_f32_e32 v43, 1.0, v45
	v_add_f32_e32 v54, 1.0, v47
	v_rcp_f32_e32 v48, v41
	v_rcp_f32_e32 v50, v43
	v_mul_f32_e32 v41, v32, v49
	v_mul_f32_e32 v43, v33, v49
	v_mul_f32_e32 v45, v34, v49
	v_mul_f32_e32 v47, v35, v49
	s_nop 0
	v_mov_b32_e32 v49, v36
	v_rcp_f32_e32 v36, v51
	v_mov_b32_e32 v51, v38
	v_rcp_f32_e32 v38, v54
	v_pk_mul_f32 v[32:33], v[48:49], v[40:41]
	v_pk_mul_f32 v[34:35], v[50:51], v[44:45]
	v_mul_f32_e32 v40, v32, v33
	v_mul_f32_e32 v41, v34, v35
	v_pk_mul_f32 v[32:33], v[36:37], v[42:43]
	v_pk_mul_f32 v[34:35], v[38:39], v[46:47]
	v_mul_f32_e32 v32, v32, v33
	v_mul_f32_e32 v33, v34, v35
	v_cvt_pk_bf16_f32 v32, v40, v32
	v_cvt_pk_bf16_f32 v33, v41, v33
	global_store_dwordx2 v[52:53], v[32:33], off offset:32
	s_branch .LBB0_2141
